# attention item mapping: 16 consecutive q-blocks of one (batch, kv head) per XCD, plus sample-attn trims
# baseline (speedup 1.0000x reference)
.LBB0_541:
	s_or_b64 exec, exec, s[22:23]
	s_xor_b64 s[10:11], s[36:37], -1
	v_readlane_b32 s16, v254, 26
	v_writelane_b32 v255, s10, 55
	v_readlane_b32 s17, v254, 27
	s_mov_b64 s[12:13], s[0:1]
	v_writelane_b32 v255, s11, 56
	s_mov_b32 s10, s74
	s_and_b64 vcc, exec, s[16:17]
	s_waitcnt lgkmcnt(0)
	s_barrier
	s_cbranch_vccz .LBB0_779
	s_load_dwordx2 s[12:13], s[12:13], 0xd0
	s_lshl_b32 s16, s10, 6
	s_ashr_i32 s17, s16, 31
	s_lshl_b64 s[16:17], s[16:17], 2
	s_and_b32 s4, s2, 7
	s_lshr_b32 s11, s2, 3
	s_and_b32 s81, s11, 15
	s_lshl_b32 s81, s81, 1
	s_lshr_b32 s11, s11, 4
	s_lshl_b32 s11, s11, 7
	s_add_i32 s81, s81, s11
	s_bfe_u32 s11, s4, 0x10001
	s_lshl_b32 s11, s11, 6
	s_add_i32 s81, s81, s11
	s_lshr_b32 s11, s4, 2
	s_lshl_b32 s11, s11, 5
	s_add_i32 s81, s81, s11
	s_and_b32 s4, s4, 1
	s_add_i32 s81, s81, s4
	s_waitcnt lgkmcnt(0)
	s_add_u32 s4, s12, s16
	s_addc_u32 s11, s13, s17
	s_add_u32 s68, s4, 0xf031600
	s_addc_u32 s69, s11, 0
	s_lshl_b32 s84, s10, 8
	s_lshl_b32 s90, s10, 10
	s_lshl_b32 s75, s10, 7
	s_ashr_i32 s11, s10, 31
	s_lshl_b32 s58, s10, 3
	s_ashr_i32 s85, s84, 31
	s_ashr_i32 s91, s90, 31
	s_lshl_b32 s59, s10, 2
	s_lshl_b64 s[92:93], s[10:11], 15
	s_or_b32 s78, s75, 2
	s_or_b32 s79, s75, 3
	s_add_i32 s80, s75, 0xffffafc0
	s_branch .LBB0_545
